# gates GEMM unit order remapped: rounds 0-1 cover prompt panels 0-63, the remainder round covers sample panels 64-66
# speedup vs baseline: 1.0023x; 1.0014x over previous
.LBB0_449:
	s_or_b64 exec, exec, s[0:1]
	s_add_u32 s20, s24, 0x5a00000
	s_addc_u32 s21, s25, 0
	s_add_u32 s10, s24, 0xc000
	v_mov_b32_e32 v8, v153
	s_waitcnt lgkmcnt(0)
	s_barrier
	s_addc_u32 s11, s25, 0
	s_and_b64 vcc, exec, s[4:5]
	v_readfirstlane_b32 s4, v8
	s_cbranch_vccnz .LBB0_468
	v_lshlrev_b32_e32 v0, 4, v8
	v_add_u32_e32 v1, 0x2000, v0
	v_ashrrev_i32_e32 v2, 31, v1
	v_lshrrev_b32_e32 v2, 22, v2
	v_add_u32_e32 v2, v1, v2
	v_ashrrev_i32_e32 v2, 10, v2
	v_mul_i32_i24_e32 v3, 0x400, v2
	v_sub_u32_e32 v1, v1, v3
	v_lshrrev_b32_e32 v3, 4, v1
	v_bitop3_b32 v1, v3, v1, 32 bitop3:0x6c
	v_ashrrev_i32_e32 v3, 31, v1
	v_lshrrev_b32_e32 v3, 26, v3
	v_add_u32_e32 v3, v1, v3
	v_lshlrev_b32_e32 v5, 3, v2
	v_ashrrev_i32_e32 v4, 6, v3
	v_and_b32_e32 v5, -16, v5
	v_and_b32_e32 v3, 0xc0, v3
	v_add_u32_e32 v5, v4, v5
	v_sub_u32_e32 v1, v1, v3
	v_mov_b32_e32 v3, 1
	v_and_b32_e32 v4, 3, v4
	s_mov_b32 s0, 0x7fffe0
	v_lshrrev_b32_e32 v6, 2, v5
	v_lshlrev_b32_e32 v7, 1, v5
	v_lshlrev_b32_e32 v2, 5, v2
	v_ashrrev_i16_sdwa v1, v3, sext(v1) dst_sel:DWORD dst_unused:UNUSED_PAD src0_sel:DWORD src1_sel:BYTE_0
	v_and_or_b32 v4, v5, s0, v4
	v_and_b32_e32 v6, 4, v6
	v_and_b32_e32 v7, 24, v7
	v_and_b32_e32 v2, 32, v2
	v_bfe_i32 v1, v1, 0, 16
	v_or3_b32 v4, v4, v6, v7
	v_add_lshl_u32 v1, v2, v1, 1
	v_lshl_add_u32 v154, v4, 9, v1
	v_lshl_add_u32 v156, v5, 11, v1
	v_bfe_i32 v1, v8, 27, 1
	v_lshrrev_b32_e32 v1, 22, v1
	v_add_u32_e32 v1, v0, v1
	v_and_b32_e32 v1, 0xfffffc00, v1
	v_sub_u32_e32 v0, v0, v1
	v_lshrrev_b32_e32 v1, 4, v0
	v_ashrrev_i32_e32 v4, 31, v8
	v_bitop3_b32 v0, v1, v0, 32 bitop3:0x6c
	v_lshrrev_b32_e32 v4, 26, v4
	v_ashrrev_i32_e32 v1, 31, v0
	v_add_u32_e32 v4, v8, v4
	v_lshrrev_b32_e32 v1, 26, v1
	v_ashrrev_i32_e32 v4, 6, v4
	v_add_u32_e32 v1, v0, v1
	v_lshlrev_b32_e32 v5, 3, v4
	s_add_u32 s3, s24, 0x500000
	v_ashrrev_i32_e32 v2, 6, v1
	v_and_b32_e32 v5, -16, v5
	s_addc_u32 s27, s25, 0
	v_add_u32_e32 v5, v2, v5
	v_and_b32_e32 v2, 3, v2
	s_ashr_i32 s40, s101, 31
	v_and_or_b32 v2, v5, s0, v2
	s_lshr_b32 s0, s40, 29
	s_add_i32 s0, s101, s0
	s_ashr_i32 s8, s4, 6
	s_ashr_i32 s1, s0, 3
	s_and_b32 s0, s0, -8
	s_ashr_i32 s5, s4, 8
	s_lshl_b32 s33, s8, 10
	s_sub_i32 s0, s101, s0
	s_cmp_lt_i32 s0, 0
	s_movk_i32 s6, 0x44
	s_cselect_b32 s9, s6, 0x43
	s_lshl_b32 s0, s0, 6
	s_add_i32 s1, s0, s1
	s_ashr_i32 s0, s1, 31
	s_lshr_b32 s0, s0, 29
	s_add_i32 s9, s1, s0
	s_ashr_i32 s0, s9, 3
	s_and_b32 s9, s9, -8
	s_sub_i32 s78, s1, s9
	v_and_b32_e32 v1, 0xc0, v1
	s_ashr_i32 s16, s78, 1
	v_sub_u32_e32 v0, v0, v1
	s_ashr_i32 s1, s0, 31
	s_ashr_i32 s17, s16, 31
	s_ashr_i32 s79, s78, 31
	v_lshrrev_b32_e32 v6, 2, v5
	v_lshlrev_b32_e32 v7, 1, v5
	v_lshlrev_b32_e32 v4, 5, v4
	v_ashrrev_i16_sdwa v0, v3, sext(v0) dst_sel:DWORD dst_unused:UNUSED_PAD src0_sel:DWORD src1_sel:BYTE_0
	s_lshl_b64 s[14:15], s[0:1], 19
	s_lshl_b64 s[16:17], s[16:17], 9
	s_lshl_b64 s[18:19], s[78:79], 17
	v_and_b32_e32 v6, 4, v6
	v_and_b32_e32 v7, 24, v7
	v_and_b32_e32 v4, 32, v4
	v_bfe_i32 v0, v0, 0, 16
	s_add_u32 s80, s3, s18
	v_or3_b32 v2, v2, v6, v7
	v_add_lshl_u32 v0, v4, v0, 1
	s_addc_u32 s81, s27, s19
	s_add_i32 s41, s33, 0
	v_lshl_add_u32 v158, v2, 9, v0
	s_add_i32 m0, s41, 0x10000
	v_lshl_add_u32 v160, v5, 11, v0
	global_load_lds_dwordx4 v158, s[80:81]
	s_add_i32 m0, s41, 0x12000
	s_add_u32 s1, s30, s14
	s_addc_u32 s9, s31, s15
	s_add_u32 s14, s80, 0x10000
	global_load_lds_dwordx4 v154, s[80:81]
	s_addc_u32 s15, s81, 0
	s_add_i32 m0, s41, 0x14000
	v_writelane_b32 v254, s10, 51
	global_load_lds_dwordx4 v158, s[14:15]
	s_add_i32 m0, s41, 0x16000
	s_add_u32 s82, s1, s16
	s_addc_u32 s83, s9, s17
	s_add_i32 s77, s41, 0x2000
	global_load_lds_dwordx4 v154, s[14:15]
	s_mov_b32 m0, s41
	s_add_u32 s14, s82, 0x40000
	global_load_lds_dwordx4 v160, s[82:83]
	s_mov_b32 m0, s77
	s_addc_u32 s15, s83, 0
	s_add_i32 s79, s41, 0x4000
	global_load_lds_dwordx4 v156, s[82:83]
	s_mov_b32 m0, s79
	s_add_i32 s86, s41, 0x6000
	global_load_lds_dwordx4 v160, s[14:15]
	s_mov_b32 m0, s86
	v_writelane_b32 v254, s11, 52
	global_load_lds_dwordx4 v156, s[14:15]
	v_writelane_b32 v254, s94, 53
	s_cmp_eq_u32 s5, 1
	v_mov_b32_e32 v159, 0
	v_writelane_b32 v254, s95, 54
	v_writelane_b32 v254, s92, 55
	s_cselect_b64 s[6:7], -1, 0
	v_mov_b32_e32 v155, v159
	v_writelane_b32 v254, s93, 56
	v_writelane_b32 v254, s91, 57
	v_mov_b32_e32 v161, v159
	v_mov_b32_e32 v157, v159
	v_writelane_b32 v254, s6, 58
	s_mov_b32 s87, 0
	v_lshl_add_u64 v[4:5], s[80:81], 0, v[158:159]
	v_lshl_add_u64 v[2:3], s[80:81], 0, v[154:155]
	v_lshl_add_u64 v[0:1], s[82:83], 0, v[160:161]
	v_writelane_b32 v254, s7, 59
	s_cmp_lg_u32 s5, 1
	v_lshl_add_u64 v[6:7], s[82:83], 0, v[156:157]
	s_cbranch_scc1 .LBB0_452
	s_barrier

.LBB0_455:
	s_add_i32 s87, s87, 1
	s_mul_i32 s1, s87, s90
	s_mul_hi_u32 s4, s87, s26
	s_add_i32 s4, s4, s1
	s_mul_i32 s1, s87, s26
	s_add_u32 s36, s1, s101
	s_addc_u32 s37, s4, s40
	v_cmp_gt_i64_e32 vcc, s[36:37], v[164:165]
	v_cmp_lt_i64_e64 s[44:45], s[36:37], v[162:163]
	s_cbranch_vccnz .LBB0_457
	s_ashr_i32 s1, s36, 31
	s_lshr_b32 s1, s1, 29
	s_add_i32 s1, s36, s1
	s_ashr_i32 s8, s1, 3
	s_and_b32 s1, s1, -8
	s_sub_i32 s1, s36, s1
	s_cmp_lt_i32 s8, 64
	s_cbranch_scc0 .Lgmap_ext
	s_lshl_b32 s1, s1, 6
	s_add_i32 s1, s1, s8
	s_ashr_i32 s56, s1, 3
	s_and_b32 s46, s1, 7
	s_branch .Lgmap_done
.Lgmap_ext:
	s_mov_b32 s46, s1
	s_mov_b32 s56, s8
.Lgmap_done:
.LBB0_457:
	s_ashr_i32 s57, s56, 31
	s_lshl_b64 s[8:9], s[56:57], 19
	s_add_u32 s1, s30, s8
	s_addc_u32 s16, s31, s9
	s_ashr_i32 s8, s46, 1
	s_ashr_i32 s9, s8, 31
	s_lshl_b64 s[8:9], s[8:9], 9
	s_add_u32 s72, s1, s8
	s_addc_u32 s73, s16, s9
	s_and_b64 s[8:9], s[44:45], exec
	s_cselect_b32 s1, s73, s83
	s_cselect_b32 s16, s72, s82
	s_ashr_i32 s47, s46, 31
	s_lshl_b64 s[8:9], s[46:47], 17
	s_add_u32 s74, s3, s8
	s_addc_u32 s75, s27, s9
	s_and_b64 s[8:9], s[44:45], exec
	v_mov_b32_e32 v0, 0
	s_cselect_b32 s17, s75, s81
	s_cselect_b32 s28, s74, s80
	s_mov_b32 s18, 0
	s_mov_b64 s[84:85], -1
	s_mov_b64 s[36:37], 0
	v_mov_b32_e32 v1, v0
	v_mov_b32_e32 v2, v0
	v_mov_b32_e32 v3, v0
	v_mov_b32_e32 v8, v0
	v_mov_b32_e32 v9, v0
	v_mov_b32_e32 v10, v0
	v_mov_b32_e32 v11, v0
	v_mov_b32_e32 v16, v0
	v_mov_b32_e32 v17, v0
	v_mov_b32_e32 v18, v0
	v_mov_b32_e32 v19, v0
	v_mov_b32_e32 v24, v0
	v_mov_b32_e32 v25, v0
	v_mov_b32_e32 v26, v0
	v_mov_b32_e32 v27, v0
	v_mov_b32_e32 v48, v0
	v_mov_b32_e32 v49, v0
	v_mov_b32_e32 v50, v0
	v_mov_b32_e32 v51, v0
	v_mov_b32_e32 v56, v0
	v_mov_b32_e32 v57, v0
	v_mov_b32_e32 v58, v0
	v_mov_b32_e32 v59, v0
	v_mov_b32_e32 v64, v0
	v_mov_b32_e32 v65, v0
	v_mov_b32_e32 v66, v0
	v_mov_b32_e32 v67, v0
	v_mov_b32_e32 v72, v0
	v_mov_b32_e32 v73, v0
	v_mov_b32_e32 v74, v0
	v_mov_b32_e32 v75, v0
	v_mov_b32_e32 v4, v0
	v_mov_b32_e32 v5, v0
	v_mov_b32_e32 v6, v0
	v_mov_b32_e32 v7, v0
	v_mov_b32_e32 v12, v0
	v_mov_b32_e32 v13, v0
	v_mov_b32_e32 v14, v0
	v_mov_b32_e32 v15, v0
	v_mov_b32_e32 v20, v0
	v_mov_b32_e32 v21, v0
	v_mov_b32_e32 v22, v0
	v_mov_b32_e32 v23, v0
	v_mov_b32_e32 v36, v0
	v_mov_b32_e32 v37, v0
	v_mov_b32_e32 v38, v0
	v_mov_b32_e32 v39, v0
	v_mov_b32_e32 v52, v0
	v_mov_b32_e32 v53, v0
	v_mov_b32_e32 v54, v0
	v_mov_b32_e32 v55, v0
	v_mov_b32_e32 v60, v0
	v_mov_b32_e32 v61, v0
	v_mov_b32_e32 v62, v0
	v_mov_b32_e32 v63, v0
	v_mov_b32_e32 v68, v0
	v_mov_b32_e32 v69, v0
	v_mov_b32_e32 v70, v0
	v_mov_b32_e32 v71, v0
	v_mov_b32_e32 v76, v0
	v_mov_b32_e32 v77, v0
	v_mov_b32_e32 v78, v0
	v_mov_b32_e32 v79, v0
	v_mov_b32_e32 v80, v0
	v_mov_b32_e32 v81, v0
	v_mov_b32_e32 v82, v0
	v_mov_b32_e32 v83, v0
	v_mov_b32_e32 v88, v0
	v_mov_b32_e32 v89, v0
	v_mov_b32_e32 v90, v0
	v_mov_b32_e32 v91, v0
	v_mov_b32_e32 v96, v0
	v_mov_b32_e32 v97, v0
	v_mov_b32_e32 v98, v0
	v_mov_b32_e32 v99, v0
	v_mov_b32_e32 v104, v0
	v_mov_b32_e32 v105, v0
	v_mov_b32_e32 v106, v0
	v_mov_b32_e32 v107, v0
	v_mov_b32_e32 v112, v0
	v_mov_b32_e32 v113, v0
	v_mov_b32_e32 v114, v0
	v_mov_b32_e32 v115, v0
	v_mov_b32_e32 v120, v0
	v_mov_b32_e32 v121, v0
	v_mov_b32_e32 v122, v0
	v_mov_b32_e32 v123, v0
	v_mov_b32_e32 v128, v0
	v_mov_b32_e32 v129, v0
	v_mov_b32_e32 v130, v0
	v_mov_b32_e32 v131, v0
	v_mov_b32_e32 v136, v0
	v_mov_b32_e32 v137, v0
	v_mov_b32_e32 v138, v0
	v_mov_b32_e32 v139, v0
	v_mov_b32_e32 v84, v0
	v_mov_b32_e32 v85, v0
	v_mov_b32_e32 v86, v0
	v_mov_b32_e32 v87, v0
	v_mov_b32_e32 v92, v0
	v_mov_b32_e32 v93, v0
	v_mov_b32_e32 v94, v0
	v_mov_b32_e32 v95, v0
	v_mov_b32_e32 v100, v0
	v_mov_b32_e32 v101, v0
	v_mov_b32_e32 v102, v0
	v_mov_b32_e32 v103, v0
	v_mov_b32_e32 v108, v0
	v_mov_b32_e32 v109, v0
	v_mov_b32_e32 v110, v0
	v_mov_b32_e32 v111, v0
	v_mov_b32_e32 v116, v0
	v_mov_b32_e32 v117, v0
	v_mov_b32_e32 v118, v0
	v_mov_b32_e32 v119, v0
	v_mov_b32_e32 v124, v0
	v_mov_b32_e32 v125, v0
	v_mov_b32_e32 v126, v0
	v_mov_b32_e32 v127, v0
	v_mov_b32_e32 v132, v0
	v_mov_b32_e32 v133, v0
	v_mov_b32_e32 v134, v0
	v_mov_b32_e32 v135, v0
	v_mov_b32_e32 v140, v0
	v_mov_b32_e32 v141, v0
	v_mov_b32_e32 v142, v0
	v_mov_b32_e32 v143, v0
